# main G1: first K iteration peeled; its first MFMA per accumulator chain takes srcC = 0, so the tile header no longer zeroes the 128 accumulators
# baseline (speedup 1.0000x reference)
.LBB0_56:
	s_ashr_i32 s95, s94, 31
	s_lshl_b64 s[6:7], s[94:95], 19
	v_readlane_b32 s9, v253, 5
	s_add_u32 s80, s9, s6
	v_readlane_b32 s6, v253, 6
	s_addc_u32 s81, s6, s7
	s_and_b64 s[6:7], s[42:43], exec
	s_cselect_b32 s9, s81, s1
	s_cselect_b32 s11, s80, s0
	s_ashr_i32 s93, s92, 31
	s_lshl_b64 s[6:7], s[92:93], 19
	v_readlane_b32 s12, v253, 61
	s_add_u32 s82, s12, s6
	v_readlane_b32 s6, v253, 62
	s_addc_u32 s83, s6, s7
	s_and_b64 s[6:7], s[42:43], exec
	s_cselect_b32 s12, s83, s5
	s_cselect_b32 s13, s82, s4
	s_add_u32 s0, s0, 0x40080
	s_addc_u32 s1, s1, 0
	s_add_u32 s14, s4, 0x100
	s_addc_u32 s15, s5, 0
	s_mov_b32 s16, -2
	s_add_u32 s4, s0, 0xfffc0080
	s_addc_u32 s5, s1, -1
	s_add_i32 s17, 0, 0x10000
	s_cmp_eq_u32 s16, 12
	s_cselect_b32 s7, s9, s5
	s_cselect_b32 s6, s11, s4
	v_add_u32_e32 v0, s17, v198
	s_cselect_b32 s5, s12, s15
	s_cselect_b32 s4, s13, s14
	s_add_i32 s20, 0, 0x14000
	ds_read_b128 v[18:21], v0
	ds_read_b128 v[22:25], v0 offset:1024
	ds_read_b128 v[34:37], v0 offset:2048
	ds_read_b128 v[38:41], v0 offset:3072
	v_add_u32_e32 v0, s20, v198
	ds_read_b128 v[146:149], v0
	ds_read_b128 v[150:153], v0 offset:1024
	ds_read_b128 v[172:175], v0 offset:2048
	ds_read_b128 v[176:179], v0 offset:3072
	v_lshl_add_u64 v[188:189], s[0:1], 0, v[168:169]
	s_add_i32 m0, s69, 0xc000
	ds_read_b128 v[180:183], v200
	ds_read_b128 v[184:187], v200 offset:1024
	ds_read_b128 v[202:205], v200 offset:2048
	ds_read_b128 v[206:209], v200 offset:3072
	ds_read_b128 v[210:213], v200 offset:4096
	ds_read_b128 v[214:217], v200 offset:5120
	ds_read_b128 v[218:221], v200 offset:6144
	ds_read_b128 v[234:237], v200 offset:7168
	global_load_lds_dwordx4 v[188:189], off
	v_lshl_add_u64 v[188:189], s[0:1], 0, v[170:171]
	s_add_i32 m0, s69, 0xe000
	s_nop 0
	global_load_lds_dwordx4 v[188:189], off
	s_waitcnt vmcnt(8)
	s_waitcnt lgkmcnt(0)
	s_barrier
	s_setprio 1
	s_waitcnt lgkmcnt(0)
	v_mfma_f32_16x16x32_bf16 v[142:145], v[18:21], v[180:183], 0
	v_mfma_f32_16x16x32_bf16 v[138:141], v[34:37], v[180:183], 0
	v_mfma_f32_16x16x32_bf16 v[126:129], v[18:21], v[202:205], 0
	v_mfma_f32_16x16x32_bf16 v[122:125], v[34:37], v[202:205], 0
	v_mfma_f32_16x16x32_bf16 v[110:113], v[18:21], v[210:213], 0
	v_mfma_f32_16x16x32_bf16 v[106:109], v[34:37], v[210:213], 0
	v_mfma_f32_16x16x32_bf16 v[94:97], v[18:21], v[218:221], 0
	v_mfma_f32_16x16x32_bf16 v[90:93], v[34:37], v[218:221], 0
	v_mfma_f32_16x16x32_bf16 v[142:145], v[22:25], v[184:187], v[142:145]
	v_mfma_f32_16x16x32_bf16 v[138:141], v[38:41], v[184:187], v[138:141]
	v_mfma_f32_16x16x32_bf16 v[126:129], v[22:25], v[206:209], v[126:129]
	v_mfma_f32_16x16x32_bf16 v[122:125], v[38:41], v[206:209], v[122:125]
	v_mfma_f32_16x16x32_bf16 v[110:113], v[22:25], v[214:217], v[110:113]
	v_mfma_f32_16x16x32_bf16 v[106:109], v[38:41], v[214:217], v[106:109]
	v_mfma_f32_16x16x32_bf16 v[94:97], v[22:25], v[234:237], v[94:97]
	v_mfma_f32_16x16x32_bf16 v[90:93], v[38:41], v[234:237], v[90:93]
	s_setprio 0
	s_setprio 1
	v_mfma_f32_16x16x32_bf16 v[134:137], v[146:149], v[180:183], 0
	v_mfma_f32_16x16x32_bf16 v[130:133], v[172:175], v[180:183], 0
	v_mfma_f32_16x16x32_bf16 v[118:121], v[146:149], v[202:205], 0
	v_mfma_f32_16x16x32_bf16 v[114:117], v[172:175], v[202:205], 0
	v_mfma_f32_16x16x32_bf16 v[102:105], v[146:149], v[210:213], 0
	v_mfma_f32_16x16x32_bf16 v[98:101], v[172:175], v[210:213], 0
	v_mfma_f32_16x16x32_bf16 v[86:89], v[146:149], v[218:221], 0
	v_mfma_f32_16x16x32_bf16 v[82:85], v[172:175], v[218:221], 0
	v_mfma_f32_16x16x32_bf16 v[134:137], v[150:153], v[184:187], v[134:137]
	v_mfma_f32_16x16x32_bf16 v[130:133], v[176:179], v[184:187], v[130:133]
	v_mfma_f32_16x16x32_bf16 v[118:121], v[150:153], v[206:209], v[118:121]
	v_mfma_f32_16x16x32_bf16 v[114:117], v[176:179], v[206:209], v[114:117]
	v_mfma_f32_16x16x32_bf16 v[102:105], v[150:153], v[214:217], v[102:105]
	v_mfma_f32_16x16x32_bf16 v[98:101], v[176:179], v[214:217], v[98:101]
	v_mfma_f32_16x16x32_bf16 v[86:89], v[150:153], v[234:237], v[86:89]
	v_mfma_f32_16x16x32_bf16 v[82:85], v[176:179], v[234:237], v[82:85]
	s_setprio 0
	s_barrier
	s_add_i32 s17, s17, s87
	v_lshl_add_u64 v[188:189], s[4:5], 0, v[158:159]
	s_mov_b32 m0, s17
	ds_read_b128 v[180:183], v200 offset:16384
	ds_read_b128 v[184:187], v200 offset:17408
	ds_read_b128 v[202:205], v200 offset:18432
	ds_read_b128 v[206:209], v200 offset:19456
	ds_read_b128 v[210:213], v200 offset:20480
	ds_read_b128 v[214:217], v200 offset:21504
	ds_read_b128 v[218:221], v200 offset:22528
	ds_read_b128 v[234:237], v200 offset:23552
	global_load_lds_dwordx4 v[188:189], off
	s_add_i32 m0, s17, 0x2000
	s_add_u32 s18, s4, 0x40000
	v_lshl_add_u64 v[222:223], s[4:5], 0, v[154:155]
	s_addc_u32 s19, s5, 0
	s_add_i32 s17, s20, s87
	global_load_lds_dwordx4 v[222:223], off
	v_lshl_add_u64 v[238:239], s[18:19], 0, v[158:159]
	s_mov_b32 m0, s17
	v_lshl_add_u64 v[240:241], s[6:7], 0, v[156:157]
	global_load_lds_dwordx4 v[238:239], off
	v_lshl_add_u64 v[238:239], s[18:19], 0, v[154:155]
	s_add_i32 m0, s17, 0x2000
	s_nop 0
	global_load_lds_dwordx4 v[238:239], off
	v_lshl_add_u64 v[238:239], s[6:7], 0, v[160:161]
	s_mov_b32 m0, s69
	s_nop 0
	global_load_lds_dwordx4 v[238:239], off
	s_mov_b32 m0, s76
	s_nop 0
	global_load_lds_dwordx4 v[240:241], off
	s_waitcnt vmcnt(8)
	s_waitcnt lgkmcnt(0)
	s_barrier
	s_setprio 1
	s_waitcnt lgkmcnt(0)
	v_mfma_f32_16x16x32_bf16 v[78:81], v[18:21], v[180:183], 0
	v_mfma_f32_16x16x32_bf16 v[74:77], v[34:37], v[180:183], 0
	v_mfma_f32_16x16x32_bf16 v[62:65], v[18:21], v[202:205], 0
	v_mfma_f32_16x16x32_bf16 v[58:61], v[34:37], v[202:205], 0
	v_mfma_f32_16x16x32_bf16 v[46:49], v[18:21], v[210:213], 0
	v_mfma_f32_16x16x32_bf16 v[42:45], v[34:37], v[210:213], 0
	v_mfma_f32_16x16x32_bf16 v[14:17], v[18:21], v[218:221], 0
	v_mfma_f32_16x16x32_bf16 v[10:13], v[34:37], v[218:221], 0
	v_mfma_f32_16x16x32_bf16 v[78:81], v[22:25], v[184:187], v[78:81]
	v_mfma_f32_16x16x32_bf16 v[74:77], v[38:41], v[184:187], v[74:77]
	v_mfma_f32_16x16x32_bf16 v[62:65], v[22:25], v[206:209], v[62:65]
	v_mfma_f32_16x16x32_bf16 v[58:61], v[38:41], v[206:209], v[58:61]
	v_mfma_f32_16x16x32_bf16 v[46:49], v[22:25], v[214:217], v[46:49]
	v_mfma_f32_16x16x32_bf16 v[42:45], v[38:41], v[214:217], v[42:45]
	v_mfma_f32_16x16x32_bf16 v[14:17], v[22:25], v[234:237], v[14:17]
	v_mfma_f32_16x16x32_bf16 v[10:13], v[38:41], v[234:237], v[10:13]
	s_setprio 0
	s_setprio 1
	v_mfma_f32_16x16x32_bf16 v[30:33], v[146:149], v[210:213], 0
	v_mfma_f32_16x16x32_bf16 v[26:29], v[172:175], v[210:213], 0
	v_mfma_f32_16x16x32_bf16 v[6:9], v[146:149], v[218:221], 0
	v_mfma_f32_16x16x32_bf16 v[2:5], v[172:175], v[218:221], 0
	v_mfma_f32_16x16x32_bf16 v[18:21], v[146:149], v[180:183], 0
	v_mfma_f32_16x16x32_bf16 v[22:25], v[172:175], v[180:183], 0
	v_mfma_f32_16x16x32_bf16 v[34:37], v[146:149], v[202:205], 0
	v_mfma_f32_16x16x32_bf16 v[38:41], v[172:175], v[202:205], 0
	v_mfma_f32_16x16x32_bf16 v[30:33], v[150:153], v[214:217], v[30:33]
	v_mfma_f32_16x16x32_bf16 v[26:29], v[176:179], v[214:217], v[26:29]
	v_mfma_f32_16x16x32_bf16 v[6:9], v[150:153], v[234:237], v[6:9]
	v_mfma_f32_16x16x32_bf16 v[2:5], v[176:179], v[234:237], v[2:5]
	v_mfma_f32_16x16x32_bf16 v[18:21], v[150:153], v[184:187], v[18:21]
	v_mfma_f32_16x16x32_bf16 v[22:25], v[176:179], v[184:187], v[22:25]
	v_mfma_f32_16x16x32_bf16 v[34:37], v[150:153], v[206:209], v[34:37]
	v_mfma_f32_16x16x32_bf16 v[38:41], v[176:179], v[206:209], v[38:41]
	s_setprio 0
	s_barrier
	s_add_i32 s17, 0, 0x18000
	v_add_u32_e32 v0, s17, v198
	s_add_i32 s18, 0, 0x1c000
	ds_read_b128 v[50:53], v0
	ds_read_b128 v[54:57], v0 offset:1024
	ds_read_b128 v[66:69], v0 offset:2048
	ds_read_b128 v[70:73], v0 offset:3072
	v_add_u32_e32 v0, s18, v198
	ds_read_b128 v[146:149], v0
	ds_read_b128 v[150:153], v0 offset:1024
	ds_read_b128 v[172:175], v0 offset:2048
	ds_read_b128 v[176:179], v0 offset:3072
	s_add_u32 s6, s6, 0x40000
	s_addc_u32 s7, s7, 0
	s_mov_b32 m0, s77
	v_lshl_add_u64 v[242:243], s[6:7], 0, v[160:161]
	ds_read_b128 v[180:183], v200 offset:32768
	ds_read_b128 v[184:187], v200 offset:33792
	ds_read_b128 v[202:205], v200 offset:34816
	ds_read_b128 v[206:209], v200 offset:35840
	ds_read_b128 v[210:213], v200 offset:36864
	ds_read_b128 v[214:217], v200 offset:37888
	ds_read_b128 v[218:221], v200 offset:38912
	ds_read_b128 v[234:237], v200 offset:39936
	global_load_lds_dwordx4 v[242:243], off
	v_lshl_add_u64 v[242:243], s[6:7], 0, v[156:157]
	s_mov_b32 m0, s96
	s_nop 0
	global_load_lds_dwordx4 v[242:243], off
	s_waitcnt vmcnt(8)
	s_waitcnt lgkmcnt(0)
	s_barrier
	s_setprio 1
	s_waitcnt lgkmcnt(0)
	v_mfma_f32_16x16x32_bf16 v[142:145], v[50:53], v[180:183], v[142:145]
	v_mfma_f32_16x16x32_bf16 v[138:141], v[66:69], v[180:183], v[138:141]
	v_mfma_f32_16x16x32_bf16 v[126:129], v[50:53], v[202:205], v[126:129]
	v_mfma_f32_16x16x32_bf16 v[122:125], v[66:69], v[202:205], v[122:125]
	v_mfma_f32_16x16x32_bf16 v[110:113], v[50:53], v[210:213], v[110:113]
	v_mfma_f32_16x16x32_bf16 v[106:109], v[66:69], v[210:213], v[106:109]
	v_mfma_f32_16x16x32_bf16 v[94:97], v[50:53], v[218:221], v[94:97]
	v_mfma_f32_16x16x32_bf16 v[90:93], v[66:69], v[218:221], v[90:93]
	v_mfma_f32_16x16x32_bf16 v[142:145], v[54:57], v[184:187], v[142:145]
	v_mfma_f32_16x16x32_bf16 v[138:141], v[70:73], v[184:187], v[138:141]
	v_mfma_f32_16x16x32_bf16 v[126:129], v[54:57], v[206:209], v[126:129]
	v_mfma_f32_16x16x32_bf16 v[122:125], v[70:73], v[206:209], v[122:125]
	v_mfma_f32_16x16x32_bf16 v[110:113], v[54:57], v[214:217], v[110:113]
	v_mfma_f32_16x16x32_bf16 v[106:109], v[70:73], v[214:217], v[106:109]
	v_mfma_f32_16x16x32_bf16 v[94:97], v[54:57], v[234:237], v[94:97]
	v_mfma_f32_16x16x32_bf16 v[90:93], v[70:73], v[234:237], v[90:93]
	s_setprio 0
	s_setprio 1
	v_mfma_f32_16x16x32_bf16 v[134:137], v[146:149], v[180:183], v[134:137]
	v_mfma_f32_16x16x32_bf16 v[130:133], v[172:175], v[180:183], v[130:133]
	v_mfma_f32_16x16x32_bf16 v[118:121], v[146:149], v[202:205], v[118:121]
	v_mfma_f32_16x16x32_bf16 v[114:117], v[172:175], v[202:205], v[114:117]
	v_mfma_f32_16x16x32_bf16 v[102:105], v[146:149], v[210:213], v[102:105]
	v_mfma_f32_16x16x32_bf16 v[98:101], v[172:175], v[210:213], v[98:101]
	v_mfma_f32_16x16x32_bf16 v[86:89], v[146:149], v[218:221], v[86:89]
	v_mfma_f32_16x16x32_bf16 v[82:85], v[172:175], v[218:221], v[82:85]
	v_mfma_f32_16x16x32_bf16 v[134:137], v[150:153], v[184:187], v[134:137]
	v_mfma_f32_16x16x32_bf16 v[130:133], v[176:179], v[184:187], v[130:133]
	v_mfma_f32_16x16x32_bf16 v[118:121], v[150:153], v[206:209], v[118:121]
	v_mfma_f32_16x16x32_bf16 v[114:117], v[176:179], v[206:209], v[114:117]
	v_mfma_f32_16x16x32_bf16 v[102:105], v[150:153], v[214:217], v[102:105]
	v_mfma_f32_16x16x32_bf16 v[98:101], v[176:179], v[214:217], v[98:101]
	v_mfma_f32_16x16x32_bf16 v[86:89], v[150:153], v[234:237], v[86:89]
	v_mfma_f32_16x16x32_bf16 v[82:85], v[176:179], v[234:237], v[82:85]
	s_setprio 0
	s_barrier
	s_add_i32 s6, s17, s87
	v_lshl_add_u64 v[188:189], v[188:189], 0, s[48:49]
	s_mov_b32 m0, s6
	ds_read_b128 v[180:183], v200 offset:49152
	ds_read_b128 v[184:187], v200 offset:50176
	ds_read_b128 v[202:205], v200 offset:51200
	ds_read_b128 v[206:209], v200 offset:52224
	ds_read_b128 v[210:213], v200 offset:53248
	ds_read_b128 v[214:217], v200 offset:54272
	ds_read_b128 v[218:221], v200 offset:55296
	ds_read_b128 v[234:237], v200 offset:56320
	global_load_lds_dwordx4 v[188:189], off
	s_add_i32 m0, s6, 0x2000
	s_add_u32 s4, s4, 0x40080
	v_lshl_add_u64 v[188:189], v[222:223], 0, s[48:49]
	s_addc_u32 s5, s5, 0
	s_add_i32 s6, s18, s87
	global_load_lds_dwordx4 v[188:189], off
	v_lshl_add_u64 v[188:189], s[4:5], 0, v[158:159]
	s_mov_b32 m0, s6
	s_nop 0
	global_load_lds_dwordx4 v[188:189], off
	v_lshl_add_u64 v[188:189], s[4:5], 0, v[154:155]
	s_add_i32 m0, s6, 0x2000
	s_nop 0
	global_load_lds_dwordx4 v[188:189], off
	v_lshl_add_u64 v[188:189], v[238:239], 0, s[48:49]
	s_mov_b32 m0, s74
	s_nop 0
	global_load_lds_dwordx4 v[188:189], off
	v_lshl_add_u64 v[188:189], v[240:241], 0, s[48:49]
	s_mov_b32 m0, s75
	s_nop 0
	global_load_lds_dwordx4 v[188:189], off
	s_waitcnt vmcnt(8)
	s_waitcnt lgkmcnt(0)
	s_barrier
	s_setprio 1
	s_waitcnt lgkmcnt(0)
	v_mfma_f32_16x16x32_bf16 v[78:81], v[50:53], v[180:183], v[78:81]
	v_mfma_f32_16x16x32_bf16 v[74:77], v[66:69], v[180:183], v[74:77]
	v_mfma_f32_16x16x32_bf16 v[62:65], v[50:53], v[202:205], v[62:65]
	v_mfma_f32_16x16x32_bf16 v[58:61], v[66:69], v[202:205], v[58:61]
	v_mfma_f32_16x16x32_bf16 v[46:49], v[50:53], v[210:213], v[46:49]
	v_mfma_f32_16x16x32_bf16 v[42:45], v[66:69], v[210:213], v[42:45]
	v_mfma_f32_16x16x32_bf16 v[14:17], v[50:53], v[218:221], v[14:17]
	v_mfma_f32_16x16x32_bf16 v[10:13], v[66:69], v[218:221], v[10:13]
	v_mfma_f32_16x16x32_bf16 v[78:81], v[54:57], v[184:187], v[78:81]
	v_mfma_f32_16x16x32_bf16 v[74:77], v[70:73], v[184:187], v[74:77]
	v_mfma_f32_16x16x32_bf16 v[62:65], v[54:57], v[206:209], v[62:65]
	v_mfma_f32_16x16x32_bf16 v[58:61], v[70:73], v[206:209], v[58:61]
	v_mfma_f32_16x16x32_bf16 v[46:49], v[54:57], v[214:217], v[46:49]
	v_mfma_f32_16x16x32_bf16 v[42:45], v[70:73], v[214:217], v[42:45]
	v_mfma_f32_16x16x32_bf16 v[14:17], v[54:57], v[234:237], v[14:17]
	v_mfma_f32_16x16x32_bf16 v[10:13], v[70:73], v[234:237], v[10:13]
	s_setprio 0
	s_setprio 1
	v_mfma_f32_16x16x32_bf16 v[18:21], v[146:149], v[180:183], v[18:21]
	v_mfma_f32_16x16x32_bf16 v[70:73], v[150:153], v[184:187], v[18:21]
	v_mfma_f32_16x16x32_bf16 v[18:21], v[172:175], v[180:183], v[22:25]
	v_mfma_f32_16x16x32_bf16 v[66:69], v[176:179], v[184:187], v[18:21]
	v_mfma_f32_16x16x32_bf16 v[18:21], v[146:149], v[202:205], v[34:37]
	v_mfma_f32_16x16x32_bf16 v[54:57], v[150:153], v[206:209], v[18:21]
	v_mfma_f32_16x16x32_bf16 v[18:21], v[172:175], v[202:205], v[38:41]
	v_mfma_f32_16x16x32_bf16 v[50:53], v[176:179], v[206:209], v[18:21]
	v_mfma_f32_16x16x32_bf16 v[18:21], v[146:149], v[210:213], v[30:33]
	v_mfma_f32_16x16x32_bf16 v[30:33], v[150:153], v[214:217], v[18:21]
	v_mfma_f32_16x16x32_bf16 v[18:21], v[172:175], v[210:213], v[26:29]
	v_mfma_f32_16x16x32_bf16 v[6:9], v[146:149], v[218:221], v[6:9]
	v_mfma_f32_16x16x32_bf16 v[2:5], v[172:175], v[218:221], v[2:5]
	v_mfma_f32_16x16x32_bf16 v[26:29], v[176:179], v[214:217], v[18:21]
	v_mfma_f32_16x16x32_bf16 v[6:9], v[150:153], v[234:237], v[6:9]
	v_mfma_f32_16x16x32_bf16 v[2:5], v[176:179], v[234:237], v[2:5]
	s_setprio 0
	s_barrier
	s_add_i32 s16, s16, 2
	s_add_u32 s0, s0, 0x100
	s_addc_u32 s1, s1, 0
	s_add_u32 s14, s14, 0x100
	s_addc_u32 s15, s15, 0
	s_cmp_gt_u32 s16, 13
	s_cbranch_scc0 .LBB0_57
